# nt (streaming) hint on the read-once f32 x loads of the P0 row conversion, on v85
# baseline (speedup 1.0000x reference)
; __device__ __forceinline__ unsigned cvt_pk_bf16(float lo, float hi) { unsigned r; asm volatile("v_cvt_pk_bf16_f32 %0, %1, %2" : "=v"(r) : "v"(lo), "v"(hi)); return r; }
; __device__ __forceinline__ void xb_rows(const float* X, bf16_t* XB, float* SS0, int gw, int NGW, int lane) {
;     for (int m0 = 4 * gw; m0 < T; m0 += 4 * NGW) { f32x4 v[4][4];
; #pragma unroll
;         for (int q = 0; q < 4; ++q)
; #pragma unroll
;             for (int j = 0; j < 4; ++j) v[q][j] = ((const f32x4*)(X + (size_t)(m0 + q) * D) + lane)[64 * j];
; #pragma unroll
;         for (int q = 0; q < 4; ++q) { float s = 0.f;
; #pragma unroll
;             for (int j = 0; j < 4; ++j) s += (v[q][j].x * v[q][j].x + v[q][j].y * v[q][j].y) + (v[q][j].z * v[q][j].z + v[q][j].w * v[q][j].w);
;             s = wave_sum(s); if (lane < 16) SS0[(size_t)lane * T + m0 + q] = (lane == 0) ? s : 0.f;
;             u32x2* o = (u32x2*)(XB + (size_t)(m0 + q) * D) + lane;
; #pragma unroll
;             for (int j = 0; j < 4; ++j) { u32x2 w; w.x = cvt_pk_bf16(v[q][j].x, v[q][j].y); w.y = cvt_pk_bf16(v[q][j].z, v[q][j].w); o[64 * j] = w; } } }
.LBB0_132:
	v_add_co_u32_e32 v16, vcc, 0xffffd000, v66
	s_nop 1
	v_addc_co_u32_e32 v17, vcc, -1, v67, vcc
	global_load_dwordx4 v[60:63], v[16:17], off offset:-3072 nt
	global_load_dwordx4 v[56:59], v[16:17], off offset:-2048 nt
	global_load_dwordx4 v[52:55], v[16:17], off offset:-1024 nt
	global_load_dwordx4 v[48:51], v[16:17], off nt
	global_load_dwordx4 v[12:15], v[66:67], off offset:-3072 nt
	global_load_dwordx4 v[8:11], v[66:67], off offset:-2048 nt
	global_load_dwordx4 v[4:7], v[66:67], off offset:-1024 nt
	global_load_dwordx4 v[0:3], v[66:67], off nt
	v_add_co_u32_e32 v16, vcc, 0xffffe000, v66
	s_waitcnt vmcnt(6)
	v_mul_f32_e32 v72, v57, v57
	v_addc_co_u32_e32 v17, vcc, -1, v67, vcc
	v_add_co_u32_e32 v70, vcc, 0xfffff000, v66
	global_load_dwordx4 v[44:47], v[16:17], off offset:-3072 nt
	global_load_dwordx4 v[40:43], v[16:17], off offset:-2048 nt
	global_load_dwordx4 v[36:39], v[16:17], off offset:-1024 nt
	global_load_dwordx4 v[32:35], v[16:17], off nt
	v_addc_co_u32_e32 v71, vcc, -1, v67, vcc
	global_load_dwordx4 v[28:31], v[70:71], off offset:-3072 nt
	global_load_dwordx4 v[24:27], v[70:71], off offset:-2048 nt
	s_waitcnt lgkmcnt(0)
	global_load_dwordx4 v[20:23], v[70:71], off offset:-1024 nt
	global_load_dwordx4 v[16:19], v[66:67], off offset:-4096 nt
	v_mul_f32_e32 v70, v61, v61
	v_mul_f32_e32 v71, v63, v63
	v_mul_f32_e32 v73, v59, v59
	s_waitcnt vmcnt(13)
	v_mul_f32_e32 v80, v53, v53
	v_mul_f32_e32 v81, v55, v55
	v_fmac_f32_e32 v70, v60, v60
	v_fmac_f32_e32 v71, v62, v62
	v_fmac_f32_e32 v72, v56, v56
	v_fmac_f32_e32 v73, v58, v58
	s_waitcnt vmcnt(12)
	v_mul_f32_e32 v82, v49, v49
	v_mul_f32_e32 v83, v51, v51
	v_fmac_f32_e32 v80, v52, v52
	v_fmac_f32_e32 v81, v54, v54
	v_add_f32_e32 v70, v70, v71
	v_add_f32_e32 v71, v72, v73
	v_fmac_f32_e32 v82, v48, v48
	v_fmac_f32_e32 v83, v50, v50
	v_add_f32_e32 v72, v80, v81
	v_add_f32_e32 v70, v70, v71
	v_add_f32_e32 v70, v70, v72
	v_add_f32_e32 v71, v82, v83
	v_add_f32_e32 v70, v70, v71
	ds_bpermute_b32 v71, v74, v70
	s_waitcnt lgkmcnt(0)
	v_add_f32_e32 v70, v70, v71
	ds_bpermute_b32 v71, v75, v70
	s_waitcnt lgkmcnt(0)
	v_add_f32_e32 v70, v70, v71
	ds_bpermute_b32 v71, v76, v70
	s_waitcnt lgkmcnt(0)
	v_add_f32_e32 v70, v70, v71
	ds_bpermute_b32 v71, v77, v70
	s_waitcnt lgkmcnt(0)
	v_add_f32_e32 v70, v70, v71
	ds_bpermute_b32 v71, v78, v70
	s_waitcnt lgkmcnt(0)
	v_add_f32_e32 v72, v70, v71
	ds_bpermute_b32 v73, v79, v72
	v_lshl_add_u64 v[70:71], s[28:29], 0, v[68:69]
	s_and_saveexec_b64 s[18:19], s[4:5]
	s_cbranch_execz .LBB0_134
	s_waitcnt lgkmcnt(0)
	v_add_f32_e32 v72, v72, v73
	v_cndmask_b32_e64 v80, 0, v72, s[6:7]
	v_add_co_u32_e32 v72, vcc, 0x5800000, v70
	s_nop 1
	v_addc_co_u32_e32 v73, vcc, 0, v71, vcc
	global_store_dword v[72:73], v80, off
